# cache policy: P7 gated-conv output stores (full-line 16-byte stores, consumed by the next phase from HBM) also non-temporal
# speedup vs baseline: 1.0030x; 1.0030x over previous
.Lp7_step0:
	v_cmp_ge_i32_e64 s[44:45], s27, v107
	v_min_i32_e32 v16, s27, v1
	v_mov_b32_e32 v167, v1
	v_ashrrev_i32_e32 v17, 6, v16
	v_cmp_gt_i32_e32 vcc, s15, v17
	v_lshl_or_b32 v166, v17, 10, v6
	v_add_u32_e32 v1, s3, v1
	v_cndmask_b32_e32 v18, v13, v14, vcc
	v_and_b32_e32 v19, v18, v17
	v_cmp_ne_u32_e32 vcc, 0, v19
	global_load_dwordx4 v[154:157], v166, s[10:11]
	global_load_dwordx4 v[162:165], v166, s[28:29]
	v_cndmask_b32_e32 v20, 0, v15, vcc
	v_cmp_ne_u32_e32 vcc, v19, v18
	v_sub_u32_e32 v20, v166, v20
	s_nop 0
	v_cndmask_b32_e32 v21, 0, v15, vcc
	v_add_u32_e32 v21, v166, v21
	global_load_dwordx4 v[150:153], v20, s[10:11]
	global_load_dwordx4 v[158:161], v21, s[10:11]
	s_cmp_eq_u64 s[44:45], 0
	s_cbranch_scc1 .LBB0_1038
	s_waitcnt vmcnt(12)
	v_lshrrev_b32_e32 v22, 10, v106
	v_cmp_gt_i32_e32 vcc, s15, v22
	v_lshlrev_b32_e32 v26, 16, v94
	v_and_b32_e32 v27, 0xffff0000, v94
	v_lshlrev_b32_e32 v28, 16, v95
	v_and_b32_e32 v29, 0xffff0000, v95
	v_lshlrev_b32_e32 v30, 16, v96
	v_and_b32_e32 v31, 0xffff0000, v96
	v_lshlrev_b32_e32 v32, 16, v97
	v_and_b32_e32 v33, 0xffff0000, v97
	v_cndmask_b32_e32 v23, v13, v14, vcc
	v_and_b32_e32 v24, v23, v22
	v_cmp_ne_u32_e64 s[46:47], 0, v24
	v_cmp_ne_u32_e64 s[48:49], v24, v23
	v_lshlrev_b32_e32 v50, 16, v102
	v_and_b32_e32 v51, 0xffff0000, v102
	v_lshlrev_b32_e32 v52, 16, v103
	v_and_b32_e32 v53, 0xffff0000, v103
	v_lshlrev_b32_e32 v54, 16, v104
	v_and_b32_e32 v55, 0xffff0000, v104
	v_lshlrev_b32_e32 v56, 16, v105
	v_and_b32_e32 v57, 0xffff0000, v105
	v_cndmask_b32_e64 v90, 0, v90, s[46:47]
	v_cndmask_b32_e64 v91, 0, v91, s[46:47]
	v_cndmask_b32_e64 v92, 0, v92, s[46:47]
	v_cndmask_b32_e64 v93, 0, v93, s[46:47]
	v_cndmask_b32_e64 v98, 0, v98, s[48:49]
	v_cndmask_b32_e64 v99, 0, v99, s[48:49]
	v_cndmask_b32_e64 v100, 0, v100, s[48:49]
	v_cndmask_b32_e64 v101, 0, v101, s[48:49]
	v_lshlrev_b32_e32 v34, 16, v90
	v_and_b32_e32 v35, 0xffff0000, v90
	v_lshlrev_b32_e32 v36, 16, v91
	v_and_b32_e32 v37, 0xffff0000, v91
	v_lshlrev_b32_e32 v38, 16, v92
	v_and_b32_e32 v39, 0xffff0000, v92
	v_lshlrev_b32_e32 v40, 16, v93
	v_and_b32_e32 v41, 0xffff0000, v93
	v_lshlrev_b32_e32 v42, 16, v98
	v_and_b32_e32 v43, 0xffff0000, v98
	v_lshlrev_b32_e32 v44, 16, v99
	v_and_b32_e32 v45, 0xffff0000, v99
	v_lshlrev_b32_e32 v46, 16, v100
	v_and_b32_e32 v47, 0xffff0000, v100
	v_lshlrev_b32_e32 v48, 16, v101
	v_and_b32_e32 v49, 0xffff0000, v101
	v_pk_mul_f32 v[58:59], v[74:75], v[26:27]
	v_pk_mul_f32 v[60:61], v[76:77], v[28:29]
	v_pk_mul_f32 v[62:63], v[78:79], v[30:31]
	v_pk_mul_f32 v[64:65], v[80:81], v[32:33]
	v_pk_fma_f32 v[58:59], v[66:67], v[34:35], v[58:59]
	v_pk_fma_f32 v[60:61], v[68:69], v[36:37], v[60:61]
	v_pk_fma_f32 v[62:63], v[70:71], v[38:39], v[62:63]
	v_pk_fma_f32 v[64:65], v[72:73], v[40:41], v[64:65]
	v_pk_fma_f32 v[58:59], v[82:83], v[42:43], v[58:59]
	v_pk_fma_f32 v[60:61], v[84:85], v[44:45], v[60:61]
	v_pk_fma_f32 v[62:63], v[86:87], v[46:47], v[62:63]
	v_pk_fma_f32 v[64:65], v[88:89], v[48:49], v[64:65]
	v_pk_mul_f32 v[58:59], v[58:59], v[50:51]
	v_pk_mul_f32 v[60:61], v[60:61], v[52:53]
	v_pk_mul_f32 v[62:63], v[62:63], v[54:55]
	v_pk_mul_f32 v[64:65], v[64:65], v[56:57]
	v_cvt_pk_bf16_f32 v94, v58, v59
	v_cvt_pk_bf16_f32 v95, v60, v61
	v_cvt_pk_bf16_f32 v96, v62, v63
	v_cvt_pk_bf16_f32 v97, v64, v65
	s_and_saveexec_b64 s[12:13], s[44:45]
	global_store_dwordx4 v106, v[94:97], s[28:29] nt
	s_mov_b64 exec, s[12:13]
.Lp7_step1:
	v_cmp_ge_i32_e64 s[44:45], s27, v127
	v_min_i32_e32 v16, s27, v1
	v_mov_b32_e32 v107, v1
	v_ashrrev_i32_e32 v17, 6, v16
	v_cmp_gt_i32_e32 vcc, s15, v17
	v_lshl_or_b32 v106, v17, 10, v6
	v_add_u32_e32 v1, s3, v1
	v_cndmask_b32_e32 v18, v13, v14, vcc
	v_and_b32_e32 v19, v18, v17
	v_cmp_ne_u32_e32 vcc, 0, v19
	global_load_dwordx4 v[94:97], v106, s[10:11]
	global_load_dwordx4 v[102:105], v106, s[28:29]
	v_cndmask_b32_e32 v20, 0, v15, vcc
	v_cmp_ne_u32_e32 vcc, v19, v18
	v_sub_u32_e32 v20, v106, v20
	s_nop 0
	v_cndmask_b32_e32 v21, 0, v15, vcc
	v_add_u32_e32 v21, v106, v21
	global_load_dwordx4 v[90:93], v20, s[10:11]
	global_load_dwordx4 v[98:101], v21, s[10:11]
	s_cmp_eq_u64 s[44:45], 0
	s_cbranch_scc1 .LBB0_1038
	s_waitcnt vmcnt(12)
	v_lshrrev_b32_e32 v22, 10, v126
	v_cmp_gt_i32_e32 vcc, s15, v22
	v_lshlrev_b32_e32 v26, 16, v114
	v_and_b32_e32 v27, 0xffff0000, v114
	v_lshlrev_b32_e32 v28, 16, v115
	v_and_b32_e32 v29, 0xffff0000, v115
	v_lshlrev_b32_e32 v30, 16, v116
	v_and_b32_e32 v31, 0xffff0000, v116
	v_lshlrev_b32_e32 v32, 16, v117
	v_and_b32_e32 v33, 0xffff0000, v117
	v_cndmask_b32_e32 v23, v13, v14, vcc
	v_and_b32_e32 v24, v23, v22
	v_cmp_ne_u32_e64 s[46:47], 0, v24
	v_cmp_ne_u32_e64 s[48:49], v24, v23
	v_lshlrev_b32_e32 v50, 16, v122
	v_and_b32_e32 v51, 0xffff0000, v122
	v_lshlrev_b32_e32 v52, 16, v123
	v_and_b32_e32 v53, 0xffff0000, v123
	v_lshlrev_b32_e32 v54, 16, v124
	v_and_b32_e32 v55, 0xffff0000, v124
	v_lshlrev_b32_e32 v56, 16, v125
	v_and_b32_e32 v57, 0xffff0000, v125
	v_cndmask_b32_e64 v110, 0, v110, s[46:47]
	v_cndmask_b32_e64 v111, 0, v111, s[46:47]
	v_cndmask_b32_e64 v112, 0, v112, s[46:47]
	v_cndmask_b32_e64 v113, 0, v113, s[46:47]
	v_cndmask_b32_e64 v118, 0, v118, s[48:49]
	v_cndmask_b32_e64 v119, 0, v119, s[48:49]
	v_cndmask_b32_e64 v120, 0, v120, s[48:49]
	v_cndmask_b32_e64 v121, 0, v121, s[48:49]
	v_lshlrev_b32_e32 v34, 16, v110
	v_and_b32_e32 v35, 0xffff0000, v110
	v_lshlrev_b32_e32 v36, 16, v111
	v_and_b32_e32 v37, 0xffff0000, v111
	v_lshlrev_b32_e32 v38, 16, v112
	v_and_b32_e32 v39, 0xffff0000, v112
	v_lshlrev_b32_e32 v40, 16, v113
	v_and_b32_e32 v41, 0xffff0000, v113
	v_lshlrev_b32_e32 v42, 16, v118
	v_and_b32_e32 v43, 0xffff0000, v118
	v_lshlrev_b32_e32 v44, 16, v119
	v_and_b32_e32 v45, 0xffff0000, v119
	v_lshlrev_b32_e32 v46, 16, v120
	v_and_b32_e32 v47, 0xffff0000, v120
	v_lshlrev_b32_e32 v48, 16, v121
	v_and_b32_e32 v49, 0xffff0000, v121
	v_pk_mul_f32 v[58:59], v[74:75], v[26:27]
	v_pk_mul_f32 v[60:61], v[76:77], v[28:29]
	v_pk_mul_f32 v[62:63], v[78:79], v[30:31]
	v_pk_mul_f32 v[64:65], v[80:81], v[32:33]
	v_pk_fma_f32 v[58:59], v[66:67], v[34:35], v[58:59]
	v_pk_fma_f32 v[60:61], v[68:69], v[36:37], v[60:61]
	v_pk_fma_f32 v[62:63], v[70:71], v[38:39], v[62:63]
	v_pk_fma_f32 v[64:65], v[72:73], v[40:41], v[64:65]
	v_pk_fma_f32 v[58:59], v[82:83], v[42:43], v[58:59]
	v_pk_fma_f32 v[60:61], v[84:85], v[44:45], v[60:61]
	v_pk_fma_f32 v[62:63], v[86:87], v[46:47], v[62:63]
	v_pk_fma_f32 v[64:65], v[88:89], v[48:49], v[64:65]
	v_pk_mul_f32 v[58:59], v[58:59], v[50:51]
	v_pk_mul_f32 v[60:61], v[60:61], v[52:53]
	v_pk_mul_f32 v[62:63], v[62:63], v[54:55]
	v_pk_mul_f32 v[64:65], v[64:65], v[56:57]
	v_cvt_pk_bf16_f32 v114, v58, v59
	v_cvt_pk_bf16_f32 v115, v60, v61
	v_cvt_pk_bf16_f32 v116, v62, v63
	v_cvt_pk_bf16_f32 v117, v64, v65
	s_and_saveexec_b64 s[12:13], s[44:45]
	global_store_dwordx4 v126, v[114:117], s[28:29] nt
	s_mov_b64 exec, s[12:13]
.Lp7_step2:
	v_cmp_ge_i32_e64 s[44:45], s27, v147
	v_min_i32_e32 v16, s27, v1
	v_mov_b32_e32 v127, v1
	v_ashrrev_i32_e32 v17, 6, v16
	v_cmp_gt_i32_e32 vcc, s15, v17
	v_lshl_or_b32 v126, v17, 10, v6
	v_add_u32_e32 v1, s3, v1
	v_cndmask_b32_e32 v18, v13, v14, vcc
	v_and_b32_e32 v19, v18, v17
	v_cmp_ne_u32_e32 vcc, 0, v19
	global_load_dwordx4 v[114:117], v126, s[10:11]
	global_load_dwordx4 v[122:125], v126, s[28:29]
	v_cndmask_b32_e32 v20, 0, v15, vcc
	v_cmp_ne_u32_e32 vcc, v19, v18
	v_sub_u32_e32 v20, v126, v20
	s_nop 0
	v_cndmask_b32_e32 v21, 0, v15, vcc
	v_add_u32_e32 v21, v126, v21
	global_load_dwordx4 v[110:113], v20, s[10:11]
	global_load_dwordx4 v[118:121], v21, s[10:11]
	s_cmp_eq_u64 s[44:45], 0
	s_cbranch_scc1 .LBB0_1038
	s_waitcnt vmcnt(12)
	v_lshrrev_b32_e32 v22, 10, v146
	v_cmp_gt_i32_e32 vcc, s15, v22
	v_lshlrev_b32_e32 v26, 16, v134
	v_and_b32_e32 v27, 0xffff0000, v134
	v_lshlrev_b32_e32 v28, 16, v135
	v_and_b32_e32 v29, 0xffff0000, v135
	v_lshlrev_b32_e32 v30, 16, v136
	v_and_b32_e32 v31, 0xffff0000, v136
	v_lshlrev_b32_e32 v32, 16, v137
	v_and_b32_e32 v33, 0xffff0000, v137
	v_cndmask_b32_e32 v23, v13, v14, vcc
	v_and_b32_e32 v24, v23, v22
	v_cmp_ne_u32_e64 s[46:47], 0, v24
	v_cmp_ne_u32_e64 s[48:49], v24, v23
	v_lshlrev_b32_e32 v50, 16, v142
	v_and_b32_e32 v51, 0xffff0000, v142
	v_lshlrev_b32_e32 v52, 16, v143
	v_and_b32_e32 v53, 0xffff0000, v143
	v_lshlrev_b32_e32 v54, 16, v144
	v_and_b32_e32 v55, 0xffff0000, v144
	v_lshlrev_b32_e32 v56, 16, v145
	v_and_b32_e32 v57, 0xffff0000, v145
	v_cndmask_b32_e64 v130, 0, v130, s[46:47]
	v_cndmask_b32_e64 v131, 0, v131, s[46:47]
	v_cndmask_b32_e64 v132, 0, v132, s[46:47]
	v_cndmask_b32_e64 v133, 0, v133, s[46:47]
	v_cndmask_b32_e64 v138, 0, v138, s[48:49]
	v_cndmask_b32_e64 v139, 0, v139, s[48:49]
	v_cndmask_b32_e64 v140, 0, v140, s[48:49]
	v_cndmask_b32_e64 v141, 0, v141, s[48:49]
	v_lshlrev_b32_e32 v34, 16, v130
	v_and_b32_e32 v35, 0xffff0000, v130
	v_lshlrev_b32_e32 v36, 16, v131
	v_and_b32_e32 v37, 0xffff0000, v131
	v_lshlrev_b32_e32 v38, 16, v132
	v_and_b32_e32 v39, 0xffff0000, v132
	v_lshlrev_b32_e32 v40, 16, v133
	v_and_b32_e32 v41, 0xffff0000, v133
	v_lshlrev_b32_e32 v42, 16, v138
	v_and_b32_e32 v43, 0xffff0000, v138
	v_lshlrev_b32_e32 v44, 16, v139
	v_and_b32_e32 v45, 0xffff0000, v139
	v_lshlrev_b32_e32 v46, 16, v140
	v_and_b32_e32 v47, 0xffff0000, v140
	v_lshlrev_b32_e32 v48, 16, v141
	v_and_b32_e32 v49, 0xffff0000, v141
	v_pk_mul_f32 v[58:59], v[74:75], v[26:27]
	v_pk_mul_f32 v[60:61], v[76:77], v[28:29]
	v_pk_mul_f32 v[62:63], v[78:79], v[30:31]
	v_pk_mul_f32 v[64:65], v[80:81], v[32:33]
	v_pk_fma_f32 v[58:59], v[66:67], v[34:35], v[58:59]
	v_pk_fma_f32 v[60:61], v[68:69], v[36:37], v[60:61]
	v_pk_fma_f32 v[62:63], v[70:71], v[38:39], v[62:63]
	v_pk_fma_f32 v[64:65], v[72:73], v[40:41], v[64:65]
	v_pk_fma_f32 v[58:59], v[82:83], v[42:43], v[58:59]
	v_pk_fma_f32 v[60:61], v[84:85], v[44:45], v[60:61]
	v_pk_fma_f32 v[62:63], v[86:87], v[46:47], v[62:63]
	v_pk_fma_f32 v[64:65], v[88:89], v[48:49], v[64:65]
	v_pk_mul_f32 v[58:59], v[58:59], v[50:51]
	v_pk_mul_f32 v[60:61], v[60:61], v[52:53]
	v_pk_mul_f32 v[62:63], v[62:63], v[54:55]
	v_pk_mul_f32 v[64:65], v[64:65], v[56:57]
	v_cvt_pk_bf16_f32 v134, v58, v59
	v_cvt_pk_bf16_f32 v135, v60, v61
	v_cvt_pk_bf16_f32 v136, v62, v63
	v_cvt_pk_bf16_f32 v137, v64, v65
	s_and_saveexec_b64 s[12:13], s[44:45]
	global_store_dwordx4 v146, v[134:137], s[28:29] nt
	s_mov_b64 exec, s[12:13]
.Lp7_step3:
	v_cmp_ge_i32_e64 s[44:45], s27, v167
	v_min_i32_e32 v16, s27, v1
	v_mov_b32_e32 v147, v1
	v_ashrrev_i32_e32 v17, 6, v16
	v_cmp_gt_i32_e32 vcc, s15, v17
	v_lshl_or_b32 v146, v17, 10, v6
	v_add_u32_e32 v1, s3, v1
	v_cndmask_b32_e32 v18, v13, v14, vcc
	v_and_b32_e32 v19, v18, v17
	v_cmp_ne_u32_e32 vcc, 0, v19
	global_load_dwordx4 v[134:137], v146, s[10:11]
	global_load_dwordx4 v[142:145], v146, s[28:29]
	v_cndmask_b32_e32 v20, 0, v15, vcc
	v_cmp_ne_u32_e32 vcc, v19, v18
	v_sub_u32_e32 v20, v146, v20
	s_nop 0
	v_cndmask_b32_e32 v21, 0, v15, vcc
	v_add_u32_e32 v21, v146, v21
	global_load_dwordx4 v[130:133], v20, s[10:11]
	global_load_dwordx4 v[138:141], v21, s[10:11]
	s_cmp_eq_u64 s[44:45], 0
	s_cbranch_scc1 .LBB0_1038
	s_waitcnt vmcnt(12)
	v_lshrrev_b32_e32 v22, 10, v166
	v_cmp_gt_i32_e32 vcc, s15, v22
	v_lshlrev_b32_e32 v26, 16, v154
	v_and_b32_e32 v27, 0xffff0000, v154
	v_lshlrev_b32_e32 v28, 16, v155
	v_and_b32_e32 v29, 0xffff0000, v155
	v_lshlrev_b32_e32 v30, 16, v156
	v_and_b32_e32 v31, 0xffff0000, v156
	v_lshlrev_b32_e32 v32, 16, v157
	v_and_b32_e32 v33, 0xffff0000, v157
	v_cndmask_b32_e32 v23, v13, v14, vcc
	v_and_b32_e32 v24, v23, v22
	v_cmp_ne_u32_e64 s[46:47], 0, v24
	v_cmp_ne_u32_e64 s[48:49], v24, v23
	v_lshlrev_b32_e32 v50, 16, v162
	v_and_b32_e32 v51, 0xffff0000, v162
	v_lshlrev_b32_e32 v52, 16, v163
	v_and_b32_e32 v53, 0xffff0000, v163
	v_lshlrev_b32_e32 v54, 16, v164
	v_and_b32_e32 v55, 0xffff0000, v164
	v_lshlrev_b32_e32 v56, 16, v165
	v_and_b32_e32 v57, 0xffff0000, v165
	v_cndmask_b32_e64 v150, 0, v150, s[46:47]
	v_cndmask_b32_e64 v151, 0, v151, s[46:47]
	v_cndmask_b32_e64 v152, 0, v152, s[46:47]
	v_cndmask_b32_e64 v153, 0, v153, s[46:47]
	v_cndmask_b32_e64 v158, 0, v158, s[48:49]
	v_cndmask_b32_e64 v159, 0, v159, s[48:49]
	v_cndmask_b32_e64 v160, 0, v160, s[48:49]
	v_cndmask_b32_e64 v161, 0, v161, s[48:49]
	v_lshlrev_b32_e32 v34, 16, v150
	v_and_b32_e32 v35, 0xffff0000, v150
	v_lshlrev_b32_e32 v36, 16, v151
	v_and_b32_e32 v37, 0xffff0000, v151
	v_lshlrev_b32_e32 v38, 16, v152
	v_and_b32_e32 v39, 0xffff0000, v152
	v_lshlrev_b32_e32 v40, 16, v153
	v_and_b32_e32 v41, 0xffff0000, v153
	v_lshlrev_b32_e32 v42, 16, v158
	v_and_b32_e32 v43, 0xffff0000, v158
	v_lshlrev_b32_e32 v44, 16, v159
	v_and_b32_e32 v45, 0xffff0000, v159
	v_lshlrev_b32_e32 v46, 16, v160
	v_and_b32_e32 v47, 0xffff0000, v160
	v_lshlrev_b32_e32 v48, 16, v161
	v_and_b32_e32 v49, 0xffff0000, v161
	v_pk_mul_f32 v[58:59], v[74:75], v[26:27]
	v_pk_mul_f32 v[60:61], v[76:77], v[28:29]
	v_pk_mul_f32 v[62:63], v[78:79], v[30:31]
	v_pk_mul_f32 v[64:65], v[80:81], v[32:33]
	v_pk_fma_f32 v[58:59], v[66:67], v[34:35], v[58:59]
	v_pk_fma_f32 v[60:61], v[68:69], v[36:37], v[60:61]
	v_pk_fma_f32 v[62:63], v[70:71], v[38:39], v[62:63]
	v_pk_fma_f32 v[64:65], v[72:73], v[40:41], v[64:65]
	v_pk_fma_f32 v[58:59], v[82:83], v[42:43], v[58:59]
	v_pk_fma_f32 v[60:61], v[84:85], v[44:45], v[60:61]
	v_pk_fma_f32 v[62:63], v[86:87], v[46:47], v[62:63]
	v_pk_fma_f32 v[64:65], v[88:89], v[48:49], v[64:65]
	v_pk_mul_f32 v[58:59], v[58:59], v[50:51]
	v_pk_mul_f32 v[60:61], v[60:61], v[52:53]
	v_pk_mul_f32 v[62:63], v[62:63], v[54:55]
	v_pk_mul_f32 v[64:65], v[64:65], v[56:57]
	v_cvt_pk_bf16_f32 v154, v58, v59
	v_cvt_pk_bf16_f32 v155, v60, v61
	v_cvt_pk_bf16_f32 v156, v62, v63
	v_cvt_pk_bf16_f32 v157, v64, v65
	s_and_saveexec_b64 s[12:13], s[44:45]
	global_store_dwordx4 v166, v[154:157], s[28:29] nt
	s_mov_b64 exec, s[12:13]
	s_branch .Lp7_step0
